# grid-barrier poll back-off trim: the four s_sleep 1 in the barrier spin loops replaced by s_nop 0
# speedup vs baseline: 1.0017x; 1.0017x over previous
; __device__ __forceinline__ unsigned xb_ld(unsigned* p)              { return __hip_atomic_load(p, __ATOMIC_RELAXED, __HIP_MEMORY_SCOPE_AGENT); }
; __device__ __forceinline__ void xcd_barrier_complete(unsigned* bar, unsigned x, unsigned& nloc, unsigned& nx) {
;     ...
;     for (;;) {
;         sum = 0u; cnt = 0u; mine = 0u;
; #pragma unroll
;         for (unsigned j = 0; j < 16; ++j) { const unsigned c = xb_ld(&bar[XB_XCNT(j)]); sum += c; cnt += (c > 0u) ? 1u : 0u; mine = (j == x) ? c : mine; }
;         if (sum == G) break;
;         __builtin_amdgcn_s_sleep(1);
;         if ((++sp & 255u) == 0u) { if (xb_ld(&bar[XB_TMO])) break; if (sp > XB_SPIN_CAP) { atomicAdd(&bar[XB_TMO], 1u); break; } }
;     }
.LBB0_17:
	flat_load_dword v26, v[0:1] offset:1024 sc1
	flat_load_dword v3, v[0:1] offset:1280 sc1
	flat_load_dword v12, v[0:1] offset:1536 sc1
	flat_load_dword v13, v[0:1] offset:1792 sc1
	flat_load_dword v14, v[0:1] offset:2048 sc1
	flat_load_dword v15, v[0:1] offset:2304 sc1
	flat_load_dword v16, v[0:1] offset:2560 sc1
	flat_load_dword v17, v[0:1] offset:2816 sc1
	flat_load_dword v18, v[0:1] offset:3072 sc1
	flat_load_dword v19, v[0:1] offset:3328 sc1
	flat_load_dword v20, v[0:1] offset:3584 sc1
	flat_load_dword v21, v[0:1] offset:3840 sc1
	flat_load_dword v22, v[4:5] sc1
	flat_load_dword v23, v[6:7] sc1
	flat_load_dword v24, v[8:9] sc1
	flat_load_dword v25, v[10:11] sc1
	s_or_b64 s[10:11], s[10:11], exec
	s_or_b64 s[8:9], s[8:9], exec
	s_waitcnt vmcnt(0) lgkmcnt(0)
	v_add_u32_e32 v27, v3, v26
	v_add_u32_e32 v27, v27, v12
	v_add_u32_e32 v27, v27, v13
	v_add_u32_e32 v27, v27, v14
	v_add_u32_e32 v27, v27, v15
	v_add_u32_e32 v27, v27, v16
	v_add_u32_e32 v27, v27, v17
	v_add_u32_e32 v27, v27, v18
	v_add_u32_e32 v27, v27, v19
	v_add_u32_e32 v27, v27, v20
	v_add_u32_e32 v27, v27, v21
	v_add_u32_e32 v27, v27, v22
	v_add_u32_e32 v27, v27, v23
	v_add_u32_e32 v27, v27, v24
	v_add_u32_e32 v27, v27, v25
	v_cmp_ne_u32_e32 vcc, s90, v27
	s_and_saveexec_b64 s[12:13], vcc
	s_cbranch_execz .LBB0_16
	s_and_b32 s2, s1, 0xff
	s_mov_b64 s[14:15], -1
	s_cmp_eq_u32 s2, 0
	s_mov_b64 s[20:21], -1
	s_mov_b64 s[18:19], -1
	s_nop 0
	s_cbranch_scc1 .LBB0_20
	s_and_saveexec_b64 s[22:23], s[20:21]
	s_cbranch_execz .LBB0_15
	s_branch .LBB0_23

; __device__ __forceinline__ unsigned xb_ld(unsigned* p)              { return __hip_atomic_load(p, __ATOMIC_RELAXED, __HIP_MEMORY_SCOPE_AGENT); }
; __device__ __forceinline__ unsigned xb_add(unsigned* p, unsigned v) { return __hip_atomic_fetch_add(p, v, __ATOMIC_RELAXED, __HIP_MEMORY_SCOPE_AGENT); }
; #define XB_SPIN(cond, bar) do { unsigned _sp = 0; while (cond) { __builtin_amdgcn_s_sleep(1); \
;     if ((++_sp & 255u) == 0u) { if (xb_ld(&(bar)[XB_TMO])) break; if (_sp > XB_SPIN_CAP) { atomicAdd(&(bar)[XB_TMO], 1u); break; } } } } while (0)
; __device__ __forceinline__ void xcd_barrier(unsigned* bar, volatile LAS unsigned* st) {
;     ...
;         const unsigned old = xb_add(&bar[XB_XSUB(x)], 1u);
;         const unsigned gen = old / nloc;
;         if (old + 1u == (gen + 1u) * nloc) {
;             __builtin_amdgcn_fence(__ATOMIC_RELEASE, "agent");
;             asm volatile("s_waitcnt vmcnt(0)" ::: "memory");
;             const unsigned og = xb_add(&bar[XB_TOP], 1u);
;             const unsigned tg = og / nx;
;             if (og + 1u == (tg + 1u) * nx) xb_add(&bar[XB_TOPGEN], 1u);
;             else XB_SPIN(xb_ld(&bar[XB_TOPGEN]) == tg, bar);
;             __builtin_amdgcn_fence(__ATOMIC_ACQUIRE, "agent");
;             xb_add(&bar[XB_XGEN(x)], 1u);
;             asm volatile("s_waitcnt vmcnt(0)" ::: "memory");
;         } else {
;             XB_SPIN(xb_ld(&bar[XB_XGEN(x)]) == gen, bar);
;             __builtin_amdgcn_fence(__ATOMIC_ACQUIRE, "agent");
;             asm volatile("s_waitcnt vmcnt(0)" ::: "memory");
;         }
.LBB0_31:
	s_and_b32 s3, s2, 0xff
	s_mov_b64 s[18:19], -1
	s_cmp_lg_u32 s3, 0
	s_mov_b64 s[20:21], -1
	s_nop 0
	s_cbranch_scc1 .LBB0_35
	v_mov_b64_e32 v[4:5], s[72:73]
	flat_load_dword v0, v[4:5] offset:512 sc1
	s_mov_b64 s[20:21], 0
	s_mov_b64 s[22:23], -1
	s_waitcnt vmcnt(0) lgkmcnt(0)
	v_cmp_eq_u32_e32 vcc, 0, v0
	s_and_saveexec_b64 s[24:25], vcc
	s_cmp_lt_u32 s2, 0x400001
	s_cselect_b64 s[16:17], -1, 0
	s_xor_b64 s[22:23], exec, -1
	s_and_b64 s[20:21], s[16:17], exec
	s_or_b64 exec, exec, s[24:25]

; __device__ __forceinline__ unsigned xb_ld(unsigned* p)              { return __hip_atomic_load(p, __ATOMIC_RELAXED, __HIP_MEMORY_SCOPE_AGENT); }
; __device__ __forceinline__ unsigned xb_add(unsigned* p, unsigned v) { return __hip_atomic_fetch_add(p, v, __ATOMIC_RELAXED, __HIP_MEMORY_SCOPE_AGENT); }
; #define XB_SPIN(cond, bar) do { unsigned _sp = 0; while (cond) { __builtin_amdgcn_s_sleep(1); \
;     if ((++_sp & 255u) == 0u) { if (xb_ld(&(bar)[XB_TMO])) break; if (_sp > XB_SPIN_CAP) { atomicAdd(&(bar)[XB_TMO], 1u); break; } } } } while (0)
; __device__ __forceinline__ void xcd_barrier(unsigned* bar, volatile LAS unsigned* st) {
;     ...
;         const unsigned old = xb_add(&bar[XB_XSUB(x)], 1u);
;         const unsigned gen = old / nloc;
;         if (old + 1u == (gen + 1u) * nloc) {
;             __builtin_amdgcn_fence(__ATOMIC_RELEASE, "agent");
;             asm volatile("s_waitcnt vmcnt(0)" ::: "memory");
;             const unsigned og = xb_add(&bar[XB_TOP], 1u);
;             const unsigned tg = og / nx;
;             if (og + 1u == (tg + 1u) * nx) xb_add(&bar[XB_TOPGEN], 1u);
;             else XB_SPIN(xb_ld(&bar[XB_TOPGEN]) == tg, bar);
;             __builtin_amdgcn_fence(__ATOMIC_ACQUIRE, "agent");
;             xb_add(&bar[XB_XGEN(x)], 1u);
;             asm volatile("s_waitcnt vmcnt(0)" ::: "memory");
;         } else {
;             XB_SPIN(xb_ld(&bar[XB_XGEN(x)]) == gen, bar);
;             __builtin_amdgcn_fence(__ATOMIC_ACQUIRE, "agent");
;             asm volatile("s_waitcnt vmcnt(0)" ::: "memory");
;         }
.LBB0_45:
	s_and_b32 s3, s2, 0xff
	s_mov_b64 s[18:19], -1
	s_cmp_lg_u32 s3, 0
	s_mov_b64 s[22:23], -1
	s_nop 0
	s_cbranch_scc0 .LBB0_47
	s_and_saveexec_b64 s[24:25], s[22:23]
	s_cbranch_execz .LBB0_44
	s_branch .LBB0_50

; #define GSYNC() xcd_barrier((unsigned*)lds_u64(&lp->bar), bst)
; __global__ void __launch_bounds__(512, 2) mega(Params p) {
;     ...
;         if (ph > lo) { if (hi > 4096) grid.sync(); else GSYNC(); }
.LBB0_66:
	s_nop 0
	global_load_dword v1, v2, s[6:7] offset:32 sc1
	s_waitcnt vmcnt(0)
	v_and_b32_e32 v1, 0xffff0000, v1
	v_cmp_ne_u32_e32 vcc, v1, v0
	s_or_b64 s[8:9], vcc, s[8:9]
	s_andn2_b64 exec, exec, s[8:9]
	s_cbranch_execnz .LBB0_66
